# norm: non-temporal hint on the one-shot split-K partial-product loads
# speedup vs baseline: 1.0130x; 1.0078x over previous
.Lnh_nohoist:
	s_cbranch_vccnz .LBB0_1033
	v_cndmask_b32_e64 v98, 0, v178, s[42:43]
	v_mov_b32_e32 v99, v1
	v_lshl_add_u64 v[98:99], s[16:17], 0, v[98:99]
	s_movk_i32 s30, 0x6000
	v_mad_u64_u32 v[100:101], s[12:13], v98, s30, v[154:155]
	v_mov_b32_e32 v98, v101
	v_mad_u64_u32 v[98:99], s[12:13], v99, s30, v[98:99]
	s_mov_b32 s12, 0x12cdc000
	s_nop 0
	v_add_co_u32_e32 v114, vcc, s12, v200
	v_mov_b32_e32 v101, v98
	s_nop 0
	v_addc_co_u32_e32 v115, vcc, 0, v201, vcc
	v_add_co_u32_e32 v116, vcc, 0x138dc000, v200
	s_nop 1
	v_addc_co_u32_e32 v117, vcc, 0, v201, vcc
	global_load_dwordx4 v[110:113], v[100:101], off
	global_load_dwordx4 v[106:109], v[100:101], off offset:1024
	global_load_dwordx4 v[102:105], v[100:101], off offset:2048
	s_nop 0
	global_load_dwordx4 v[98:101], v[100:101], off offset:3072
	s_nop 0
	global_load_dwordx2 v[126:127], v[114:115], off nt
	global_load_dwordx2 v[122:123], v[114:115], off offset:512 nt
	global_load_dwordx2 v[118:119], v[114:115], off offset:1024 nt
	s_nop 0
	global_load_dwordx2 v[114:115], v[114:115], off offset:1536 nt
	s_nop 0
	global_load_dwordx2 v[128:129], v[116:117], off nt
	global_load_dwordx2 v[124:125], v[116:117], off offset:512 nt
	global_load_dwordx2 v[120:121], v[116:117], off offset:1024 nt
	s_nop 0
	global_load_dwordx2 v[116:117], v[116:117], off offset:1536 nt
	s_and_saveexec_b64 s[42:43], s[40:41]
	s_cbranch_execz .LBB0_1030
	v_lshrrev_b32_e32 v10, 10, v198
	v_add_u32_e32 v10, 1, v10
	v_cmp_lt_i32_e32 vcc, s91, v196
	v_mov_b32_e32 v11, v1
	v_ashrrev_i32_e32 v197, 31, v196
	v_cndmask_b32_e32 v10, 0, v10, vcc
	v_lshl_add_u64 v[10:11], s[16:17], 0, v[10:11]
	v_mad_u64_u32 v[38:39], s[12:13], v10, s30, v[154:155]
	v_lshlrev_b64 v[12:13], 11, v[196:197]
	v_mov_b32_e32 v10, v39
	v_lshl_add_u64 v[188:189], s[0:1], 0, v[12:13]
	v_lshl_add_u64 v[190:191], s[18:19], 0, v[12:13]
	v_mad_u64_u32 v[10:11], s[12:13], v11, s30, v[10:11]
	v_mov_b32_e32 v165, v1
	v_mov_b32_e32 v167, v1
	v_mov_b32_e32 v169, v1
	v_mov_b32_e32 v39, v10
	v_lshl_add_u64 v[30:31], v[188:189], 0, v[164:165]
	v_lshl_add_u64 v[32:33], v[190:191], 0, v[164:165]
	v_lshl_add_u64 v[40:41], v[188:189], 0, v[166:167]
	v_lshl_add_u64 v[186:187], v[190:191], 0, v[166:167]
	v_lshl_add_u64 v[192:193], v[188:189], 0, v[168:169]
	v_lshl_add_u64 v[194:195], v[190:191], 0, v[168:169]
	v_mov_b32_e32 v177, v1
	global_load_dwordx4 v[10:13], v[38:39], off
	global_load_dwordx4 v[14:17], v[38:39], off offset:1024
	global_load_dwordx2 v[180:181], v[30:31], off nt
	global_load_dwordx2 v[184:185], v[32:33], off nt
	global_load_dwordx2 v[182:183], v[40:41], off nt
	s_nop 0
	global_load_dwordx2 v[186:187], v[186:187], off nt
	s_nop 0
	global_load_dwordx4 v[30:33], v[38:39], off offset:2048
	s_nop 0
	global_load_dwordx4 v[38:41], v[38:39], off offset:3072
	v_lshl_add_u64 v[228:229], v[188:189], 0, v[176:177]
	v_lshl_add_u64 v[230:231], v[190:191], 0, v[176:177]
	global_load_dwordx2 v[188:189], v[192:193], off nt
	s_nop 0
	global_load_dwordx2 v[192:193], v[194:195], off nt
	global_load_dwordx2 v[190:191], v[228:229], off nt
	s_nop 0
	global_load_dwordx2 v[194:195], v[230:231], off nt
